# static priority raise for the OLDER wave half (waves 0-3): per-half copies of the six GEMM K-loops (mirror of the previous)
# speedup vs baseline: 1.0051x; 1.0051x over previous
;     __host__ __device__ bool next(int i, Unit& u) const { if (!so.next(i >> 1, u)) return false; u.k0 = (i & 1) * 512; return true; }
;     __host__ __device__ bool next(int i, Unit& u) const { if (!so.next(i, u)) return false; u.pe = main_tile(u.pn); return true; }
;     __host__ __device__ bool next(int i, Unit& u) const { if (start + i * stride >= limit) return false; if (!so.next(i, u)) return false; u.pe = late_tile(u.pn); return true; }
; template <class Epi, class Sched, bool ALIGN_EPI = false, bool SP2 = false>
; __device__ __forceinline__ void gemm_phase(PG8_LAS unsigned char* lds, const Gemm g, const Sched& S, const Epi& E) {
;     ...
;         const bool has_next = S.next(ui + 1, nxt);
;         const char* nA = has_next ? (const char*)g.A + (size_t)nxt.pm * tstepA + (size_t)nxt.k0 * 2 : cA; const char* nB = has_next ? (const char*)g.Bt + (size_t)nxt.pn * tstepB + (size_t)nxt.k0 * 2 : cB;
;     ...
;         if (!keep_) {
; #pragma unroll
;         for (int a = 0; a < 2; ++a)
; #pragma unroll
;             for (int b = 0; b < 2; ++b)
; #pragma unroll
;                 for (int m = 0; m < 4; ++m)
; #pragma unroll
;                     for (int n = 0; n < 2; ++n) acc[a][b][m][n] = (f32x4){0.f, 0.f, 0.f, 0.f};
.LBB0_134:
	s_ashr_i32 s51, s50, 31
	s_lshl_b64 s[16:17], s[50:51], 19
	s_add_u32 s66, s20, s16
	s_addc_u32 s67, s21, s17
	s_and_b64 s[16:17], s[8:9], exec
	s_cselect_b32 s11, s67, s13
	s_cselect_b32 s33, s66, s12
	s_ashr_i32 s49, s48, 31
	s_lshl_b64 s[16:17], s[48:49], 19
	s_add_u32 s68, s64, s16
	s_addc_u32 s69, s65, s17
	s_and_b64 s[16:17], s[8:9], exec
	s_cselect_b32 s36, s69, s15
	s_cselect_b32 s37, s68, s14
	s_add_u32 s12, s12, 0x40080
	s_addc_u32 s13, s13, 0
	s_add_u32 s38, s14, 0x100
	v_mov_b32_e32 v2, 0
	s_addc_u32 s49, s15, 0
	s_mov_b32 s51, -2
	v_mov_b32_e32 v3, v2
	v_mov_b32_e32 v4, v2
	v_mov_b32_e32 v5, v2
	v_mov_b32_e32 v10, v2
	v_mov_b32_e32 v11, v2
	v_mov_b32_e32 v12, v2
	v_mov_b32_e32 v13, v2
	v_mov_b32_e32 v18, v2
	v_mov_b32_e32 v19, v2
	v_mov_b32_e32 v20, v2
	v_mov_b32_e32 v21, v2
	v_mov_b32_e32 v26, v2
	v_mov_b32_e32 v27, v2
	v_mov_b32_e32 v28, v2
	v_mov_b32_e32 v29, v2
	v_mov_b32_e32 v34, v2
	v_mov_b32_e32 v35, v2
	v_mov_b32_e32 v36, v2
	v_mov_b32_e32 v37, v2
	v_mov_b32_e32 v42, v2
	v_mov_b32_e32 v43, v2
	v_mov_b32_e32 v44, v2
	v_mov_b32_e32 v45, v2
	v_mov_b32_e32 v50, v2
	v_mov_b32_e32 v51, v2
	v_mov_b32_e32 v52, v2
	v_mov_b32_e32 v53, v2
	v_mov_b32_e32 v58, v2
	v_mov_b32_e32 v59, v2
	v_mov_b32_e32 v60, v2
	v_mov_b32_e32 v61, v2
	v_mov_b32_e32 v6, v2
	v_mov_b32_e32 v7, v2
	v_mov_b32_e32 v8, v2
	v_mov_b32_e32 v9, v2
	v_mov_b32_e32 v14, v2
	v_mov_b32_e32 v15, v2
	v_mov_b32_e32 v16, v2
	v_mov_b32_e32 v17, v2
	v_mov_b32_e32 v22, v2
	v_mov_b32_e32 v23, v2
	v_mov_b32_e32 v24, v2
	v_mov_b32_e32 v25, v2
	v_mov_b32_e32 v30, v2
	v_mov_b32_e32 v31, v2
	v_mov_b32_e32 v32, v2
	v_mov_b32_e32 v33, v2
	v_mov_b32_e32 v38, v2
	v_mov_b32_e32 v39, v2
	v_mov_b32_e32 v40, v2
	v_mov_b32_e32 v41, v2
	v_mov_b32_e32 v46, v2
	v_mov_b32_e32 v47, v2
	v_mov_b32_e32 v48, v2
	v_mov_b32_e32 v49, v2
	v_mov_b32_e32 v54, v2
	v_mov_b32_e32 v55, v2
	v_mov_b32_e32 v56, v2
	v_mov_b32_e32 v57, v2
	v_mov_b32_e32 v62, v2
	v_mov_b32_e32 v63, v2
	v_mov_b32_e32 v64, v2
	v_mov_b32_e32 v65, v2
	v_mov_b32_e32 v66, v2
	v_mov_b32_e32 v67, v2
	v_mov_b32_e32 v68, v2
	v_mov_b32_e32 v69, v2
	v_mov_b32_e32 v74, v2
	v_mov_b32_e32 v75, v2
	v_mov_b32_e32 v76, v2
	v_mov_b32_e32 v77, v2
	v_mov_b32_e32 v82, v2
	v_mov_b32_e32 v83, v2
	v_mov_b32_e32 v84, v2
	v_mov_b32_e32 v85, v2
	v_mov_b32_e32 v90, v2
	v_mov_b32_e32 v91, v2
	v_mov_b32_e32 v92, v2
	v_mov_b32_e32 v93, v2
	v_mov_b32_e32 v98, v2
	v_mov_b32_e32 v99, v2
	v_mov_b32_e32 v100, v2
	v_mov_b32_e32 v101, v2
	v_mov_b32_e32 v106, v2
	v_mov_b32_e32 v107, v2
	v_mov_b32_e32 v108, v2
	v_mov_b32_e32 v109, v2
	v_mov_b32_e32 v114, v2
	v_mov_b32_e32 v115, v2
	v_mov_b32_e32 v116, v2
	v_mov_b32_e32 v117, v2
	v_mov_b32_e32 v122, v2
	v_mov_b32_e32 v123, v2
	v_mov_b32_e32 v124, v2
	v_mov_b32_e32 v125, v2
	v_mov_b32_e32 v70, v2
	v_mov_b32_e32 v71, v2
	v_mov_b32_e32 v72, v2
	v_mov_b32_e32 v73, v2
	v_mov_b32_e32 v78, v2
	v_mov_b32_e32 v79, v2
	v_mov_b32_e32 v80, v2
	v_mov_b32_e32 v81, v2
	v_mov_b32_e32 v86, v2
	v_mov_b32_e32 v87, v2
	v_mov_b32_e32 v88, v2
	v_mov_b32_e32 v89, v2
	v_mov_b32_e32 v94, v2
	v_mov_b32_e32 v95, v2
	v_mov_b32_e32 v96, v2
	v_mov_b32_e32 v97, v2
	v_mov_b32_e32 v102, v2
	v_mov_b32_e32 v103, v2
	v_mov_b32_e32 v104, v2
	v_mov_b32_e32 v105, v2
	v_mov_b32_e32 v110, v2
	v_mov_b32_e32 v111, v2
	v_mov_b32_e32 v112, v2
	v_mov_b32_e32 v113, v2
	v_mov_b32_e32 v118, v2
	v_mov_b32_e32 v119, v2
	v_mov_b32_e32 v120, v2
	v_mov_b32_e32 v121, v2
	v_mov_b32_e32 v126, v2
	v_mov_b32_e32 v127, v2
	v_mov_b32_e32 v128, v2
	v_mov_b32_e32 v129, v2
	s_cmp_lg_u32 s101, 0
	s_cbranch_scc0 .Lph135_y

;     __host__ __device__ bool next(int i, Unit& u) const { if (!so.next(i >> 1, u)) return false; u.k0 = (i & 1) * 512; return true; }
;     __host__ __device__ bool next(int i, Unit& u) const { if (!so.next(i, u)) return false; u.pe = main_tile(u.pn); return true; }
;     __host__ __device__ bool next(int i, Unit& u) const { if (start + i * stride >= limit) return false; if (!so.next(i, u)) return false; u.pe = late_tile(u.pn); return true; }
; template <class Epi, class Sched, bool ALIGN_EPI = false, bool SP2 = false>
; __device__ __forceinline__ void gemm_phase(PG8_LAS unsigned char* lds, const Gemm g, const Sched& S, const Epi& E) {
;     ...
;         const bool has_next = S.next(ui + 1, nxt);
;         const char* nA = has_next ? (const char*)g.A + (size_t)nxt.pm * tstepA + (size_t)nxt.k0 * 2 : cA; const char* nB = has_next ? (const char*)g.Bt + (size_t)nxt.pn * tstepB + (size_t)nxt.k0 * 2 : cB;
;     ...
;         if (!keep_) {
; #pragma unroll
;         for (int a = 0; a < 2; ++a)
; #pragma unroll
;             for (int b = 0; b < 2; ++b)
; #pragma unroll
;                 for (int m = 0; m < 4; ++m)
; #pragma unroll
;                     for (int n = 0; n < 2; ++n) acc[a][b][m][n] = (f32x4){0.f, 0.f, 0.f, 0.f};
.LBB0_690:
	s_ashr_i32 s79, s78, 31
	s_lshl_b64 s[66:67], s[78:79], 19
	s_add_u32 s82, s20, s66
	s_addc_u32 s83, s21, s67
	s_and_b64 s[66:67], s[80:81], exec
	s_cselect_b32 s3, s83, s9
	s_cselect_b32 s7, s82, s8
	s_ashr_i32 s77, s76, 31
	s_lshl_b64 s[66:67], s[76:77], 19
	s_mov_b32 s42, s84
	s_add_u32 s84, s84, s66
	s_addc_u32 s85, s5, s67
	s_and_b64 s[66:67], s[80:81], exec
	s_cselect_b32 s33, s85, s11
	s_cselect_b32 s35, s84, s10
	s_add_u32 s8, s8, 0x40080
	s_addc_u32 s9, s9, 0
	s_add_u32 s46, s10, 0x100
	v_mov_b32_e32 v2, 0
	s_addc_u32 s66, s11, 0
	s_mov_b32 s67, -2
	v_mov_b32_e32 v3, v2
	v_mov_b32_e32 v4, v2
	v_mov_b32_e32 v5, v2
	v_mov_b32_e32 v10, v2
	v_mov_b32_e32 v11, v2
	v_mov_b32_e32 v12, v2
	v_mov_b32_e32 v13, v2
	s_waitcnt vmcnt(0)
	v_mov_b32_e32 v18, v2
	v_mov_b32_e32 v19, v2
	v_mov_b32_e32 v20, v2
	v_mov_b32_e32 v21, v2
	v_mov_b32_e32 v26, v2
	v_mov_b32_e32 v27, v2
	v_mov_b32_e32 v28, v2
	v_mov_b32_e32 v29, v2
	v_mov_b32_e32 v34, v2
	v_mov_b32_e32 v35, v2
	v_mov_b32_e32 v36, v2
	v_mov_b32_e32 v37, v2
	v_mov_b32_e32 v42, v2
	v_mov_b32_e32 v43, v2
	v_mov_b32_e32 v44, v2
	v_mov_b32_e32 v45, v2
	v_mov_b32_e32 v50, v2
	v_mov_b32_e32 v51, v2
	v_mov_b32_e32 v52, v2
	v_mov_b32_e32 v53, v2
	v_mov_b32_e32 v58, v2
	v_mov_b32_e32 v59, v2
	v_mov_b32_e32 v60, v2
	v_mov_b32_e32 v61, v2
	v_mov_b32_e32 v6, v2
	v_mov_b32_e32 v7, v2
	v_mov_b32_e32 v8, v2
	v_mov_b32_e32 v9, v2
	v_mov_b32_e32 v14, v2
	v_mov_b32_e32 v15, v2
	v_mov_b32_e32 v16, v2
	v_mov_b32_e32 v17, v2
	v_mov_b32_e32 v22, v2
	v_mov_b32_e32 v23, v2
	v_mov_b32_e32 v24, v2
	v_mov_b32_e32 v25, v2
	v_mov_b32_e32 v30, v2
	v_mov_b32_e32 v31, v2
	v_mov_b32_e32 v32, v2
	v_mov_b32_e32 v33, v2
	v_mov_b32_e32 v38, v2
	v_mov_b32_e32 v39, v2
	v_mov_b32_e32 v40, v2
	v_mov_b32_e32 v41, v2
	v_mov_b32_e32 v46, v2
	v_mov_b32_e32 v47, v2
	v_mov_b32_e32 v48, v2
	v_mov_b32_e32 v49, v2
	v_mov_b32_e32 v54, v2
	v_mov_b32_e32 v55, v2
	v_mov_b32_e32 v56, v2
	v_mov_b32_e32 v57, v2
	v_mov_b32_e32 v62, v2
	v_mov_b32_e32 v63, v2
	v_mov_b32_e32 v64, v2
	v_mov_b32_e32 v65, v2
	v_mov_b32_e32 v66, v2
	v_mov_b32_e32 v67, v2
	v_mov_b32_e32 v68, v2
	v_mov_b32_e32 v69, v2
	v_mov_b32_e32 v74, v2
	v_mov_b32_e32 v75, v2
	v_mov_b32_e32 v76, v2
	v_mov_b32_e32 v77, v2
	v_mov_b32_e32 v82, v2
	v_mov_b32_e32 v83, v2
	v_mov_b32_e32 v84, v2
	v_mov_b32_e32 v85, v2
	v_mov_b32_e32 v90, v2
	v_mov_b32_e32 v91, v2
	v_mov_b32_e32 v92, v2
	v_mov_b32_e32 v93, v2
	v_mov_b32_e32 v98, v2
	v_mov_b32_e32 v99, v2
	v_mov_b32_e32 v100, v2
	v_mov_b32_e32 v101, v2
	v_mov_b32_e32 v106, v2
	v_mov_b32_e32 v107, v2
	v_mov_b32_e32 v108, v2
	v_mov_b32_e32 v109, v2
	v_mov_b32_e32 v114, v2
	v_mov_b32_e32 v115, v2
	v_mov_b32_e32 v116, v2
	v_mov_b32_e32 v117, v2
	v_mov_b32_e32 v122, v2
	v_mov_b32_e32 v123, v2
	v_mov_b32_e32 v124, v2
	v_mov_b32_e32 v125, v2
	v_mov_b32_e32 v70, v2
	v_mov_b32_e32 v71, v2
	v_mov_b32_e32 v72, v2
	v_mov_b32_e32 v73, v2
	v_mov_b32_e32 v78, v2
	v_mov_b32_e32 v79, v2
	v_mov_b32_e32 v80, v2
	v_mov_b32_e32 v81, v2
	v_mov_b32_e32 v86, v2
	v_mov_b32_e32 v87, v2
	v_mov_b32_e32 v88, v2
	v_mov_b32_e32 v89, v2
	v_mov_b32_e32 v94, v2
	v_mov_b32_e32 v95, v2
	v_mov_b32_e32 v96, v2
	v_mov_b32_e32 v97, v2
	v_mov_b32_e32 v102, v2
	v_mov_b32_e32 v103, v2
	v_mov_b32_e32 v104, v2
	v_mov_b32_e32 v105, v2
	v_mov_b32_e32 v110, v2
	v_mov_b32_e32 v111, v2
	v_mov_b32_e32 v112, v2
	v_mov_b32_e32 v113, v2
	v_mov_b32_e32 v118, v2
	v_mov_b32_e32 v119, v2
	v_mov_b32_e32 v120, v2
	v_mov_b32_e32 v121, v2
	v_mov_b32_e32 v126, v2
	v_mov_b32_e32 v127, v2
	v_mov_b32_e32 v128, v2
	v_mov_b32_e32 v129, v2
	s_cmp_lg_u32 s101, 0
	s_cbranch_scc0 .Lph691_y

;     __host__ __device__ bool next(int i, Unit& u) const { if (!so.next(i >> 1, u)) return false; u.k0 = (i & 1) * 512; return true; }
;     __host__ __device__ bool next(int i, Unit& u) const { if (!so.next(i, u)) return false; u.pe = main_tile(u.pn); return true; }
;     __host__ __device__ bool next(int i, Unit& u) const { if (start + i * stride >= limit) return false; if (!so.next(i, u)) return false; u.pe = late_tile(u.pn); return true; }
; template <class Epi, class Sched, bool ALIGN_EPI = false, bool SP2 = false>
; __device__ __forceinline__ void gemm_phase(PG8_LAS unsigned char* lds, const Gemm g, const Sched& S, const Epi& E) {
;     ...
;         const bool has_next = S.next(ui + 1, nxt);
;         const char* nA = has_next ? (const char*)g.A + (size_t)nxt.pm * tstepA + (size_t)nxt.k0 * 2 : cA; const char* nB = has_next ? (const char*)g.Bt + (size_t)nxt.pn * tstepB + (size_t)nxt.k0 * 2 : cB;
.LBB0_962:
	s_ashr_i32 s39, s38, 31
	s_lshl_b64 s[40:41], s[38:39], 20
	s_add_u32 s31, s10, s40
	s_addc_u32 s39, s11, s41
	s_ashr_i32 s37, s36, 31
	s_lshl_b64 s[46:47], s[36:37], 1
	s_add_u32 s40, s31, s46
	s_addc_u32 s41, s39, s47
	s_and_b64 s[68:69], s[0:1], exec
	s_cselect_b32 s37, s41, s65
	s_cselect_b32 s39, s40, s64
	s_ashr_i32 s31, s30, 31
	s_lshl_b64 s[68:69], s[30:31], 19
	s_add_u32 s31, s22, s68
	s_addc_u32 s49, s23, s69
	s_add_u32 s46, s31, s46
	s_addc_u32 s47, s49, s47
	s_and_b64 s[68:69], s[0:1], exec
	s_cselect_b32 s31, s47, s67
	s_cselect_b32 s49, s46, s66
	s_add_u32 s64, s64, 0x80080
	s_addc_u32 s65, s65, 0
	s_add_u32 s70, s66, 0x100
	s_addc_u32 s71, s67, 0
	s_mov_b32 s72, -2
	s_cmp_lg_u32 s101, 0
	s_cbranch_scc0 .Lph963_y

;     __host__ __device__ bool next(int i, Unit& u) const { if (!so.next(i >> 1, u)) return false; u.k0 = (i & 1) * 512; return true; }
;     __host__ __device__ bool next(int i, Unit& u) const { if (!so.next(i, u)) return false; u.pe = main_tile(u.pn); return true; }
;     __host__ __device__ bool next(int i, Unit& u) const { if (start + i * stride >= limit) return false; if (!so.next(i, u)) return false; u.pe = late_tile(u.pn); return true; }
; template <class Epi, class Sched, bool ALIGN_EPI = false, bool SP2 = false>
; __device__ __forceinline__ void gemm_phase(PG8_LAS unsigned char* lds, const Gemm g, const Sched& S, const Epi& E) {
;     ...
;         const bool has_next = S.next(ui + 1, nxt);
;         const char* nA = has_next ? (const char*)g.A + (size_t)nxt.pm * tstepA + (size_t)nxt.k0 * 2 : cA; const char* nB = has_next ? (const char*)g.Bt + (size_t)nxt.pn * tstepB + (size_t)nxt.k0 * 2 : cB;
.LBB0_1087:
	s_add_u32 s67, s40, 0x100
	s_addc_u32 s68, s41, 0
	s_ashr_i32 s31, s30, 31
	s_lshl_b64 s[36:37], s[30:31], 19
	s_add_u32 s38, s8, s36
	s_addc_u32 s39, s9, s37
	s_and_b64 s[36:37], s[6:7], exec
	s_cselect_b32 s31, s39, s23
	s_cselect_b32 s69, s38, s22
	s_ashr_i32 s29, s28, 31
	s_lshl_b64 s[36:37], s[28:29], 19
	s_add_u32 s36, s16, s36
	s_addc_u32 s37, s17, s37
	s_and_b64 s[46:47], s[6:7], exec
	s_cselect_b32 s29, s37, s41
	s_cselect_b32 s70, s36, s40
	v_lshl_add_u64 v[146:147], s[22:23], 0, v[138:139]
	v_lshl_add_u64 v[148:149], s[22:23], 0, v[140:141]
	s_mov_b32 s71, -2
	s_mov_b64 s[40:41], 0
	s_cmp_lg_u32 s101, 0
	s_cbranch_scc0 .Lph1088_y

; template <class Epi, class Sched, bool ALIGN_EPI = false, bool SP2 = false>
; __device__ __forceinline__ void gemm_phase(PG8_LAS unsigned char* lds, const Gemm g, const Sched& S, const Epi& E) {
;     ...
;         const char* nA = has_next ? (const char*)g.A + (size_t)nxt.pm * tstepA + (size_t)nxt.k0 * 2 : cA; const char* nB = has_next ? (const char*)g.Bt + (size_t)nxt.pn * tstepB + (size_t)nxt.k0 * 2 : cB;
;         for (int t = 0; t < nt; t += 2) {
;             const bool last = (t == nt - 2);
;             const char* a1 = cA + (size_t)(t + 1) * kstepA;
;             const char* a2 = last ? nA : cA + (size_t)(t + 2) * kstepA; const char* b2 = last ? nB : cB + (size_t)(t + 2) * kstep;
;             const char* a3 = a2 + kstepA; const char* b3 = b2 + kstep;
;     ...
;         if (!keep_) {
; #pragma unroll
;         for (int a = 0; a < 2; ++a)
; #pragma unroll
;             for (int b = 0; b < 2; ++b)
; #pragma unroll
;                 for (int m = 0; m < 4; ++m)
; #pragma unroll
;                     for (int n = 0; n < 2; ++n) acc[a][b][m][n] = (f32x4){0.f, 0.f, 0.f, 0.f};
;         }
;         cur = nxt; cA = nA; cB = nB; ++ui;
.LBB0_1243:
	s_ashr_i32 s19, s18, 31
	s_lshl_b64 s[22:23], s[18:19], 19
	s_add_u32 s22, s20, s22
	s_addc_u32 s23, s21, s23
	s_and_b64 s[24:25], s[0:1], exec
	s_cselect_b32 s19, s23, s31
	s_cselect_b32 s51, s22, s30
	s_ashr_i32 s17, s16, 31
	s_lshl_b64 s[24:25], s[16:17], 19
	s_add_u32 s24, s14, s24
	s_addc_u32 s25, s15, s25
	s_and_b64 s[38:39], s[0:1], exec
	s_cselect_b32 s17, s25, s37
	s_cselect_b32 s62, s24, s36
	s_add_u32 s30, s30, 0x40080
	s_addc_u32 s31, s31, 0
	s_add_u32 s63, s36, 0x100
	v_mov_b32_e32 v2, 0
	s_addc_u32 s64, s37, 0
	s_mov_b32 s65, -2
	v_mov_b32_e32 v3, v2
	v_mov_b32_e32 v4, v2
	v_mov_b32_e32 v5, v2
	v_mov_b32_e32 v6, v2
	v_mov_b32_e32 v7, v2
	v_mov_b32_e32 v8, v2
	v_mov_b32_e32 v9, v2
	v_mov_b32_e32 v18, v2
	v_mov_b32_e32 v19, v2
	v_mov_b32_e32 v20, v2
	v_mov_b32_e32 v21, v2
	v_mov_b32_e32 v22, v2
	v_mov_b32_e32 v23, v2
	v_mov_b32_e32 v24, v2
	v_mov_b32_e32 v25, v2
	v_mov_b32_e32 v34, v2
	v_mov_b32_e32 v35, v2
	v_mov_b32_e32 v36, v2
	v_mov_b32_e32 v37, v2
	v_mov_b32_e32 v38, v2
	v_mov_b32_e32 v39, v2
	v_mov_b32_e32 v40, v2
	v_mov_b32_e32 v41, v2
	v_mov_b32_e32 v50, v2
	v_mov_b32_e32 v51, v2
	v_mov_b32_e32 v52, v2
	v_mov_b32_e32 v53, v2
	v_mov_b32_e32 v54, v2
	v_mov_b32_e32 v55, v2
	v_mov_b32_e32 v56, v2
	v_mov_b32_e32 v57, v2
	v_mov_b32_e32 v10, v2
	v_mov_b32_e32 v11, v2
	v_mov_b32_e32 v12, v2
	v_mov_b32_e32 v13, v2
	v_mov_b32_e32 v14, v2
	v_mov_b32_e32 v15, v2
	v_mov_b32_e32 v16, v2
	v_mov_b32_e32 v17, v2
	v_mov_b32_e32 v26, v2
	v_mov_b32_e32 v27, v2
	v_mov_b32_e32 v28, v2
	v_mov_b32_e32 v29, v2
	v_mov_b32_e32 v30, v2
	v_mov_b32_e32 v31, v2
	v_mov_b32_e32 v32, v2
	v_mov_b32_e32 v33, v2
	v_mov_b32_e32 v42, v2
	v_mov_b32_e32 v43, v2
	v_mov_b32_e32 v44, v2
	v_mov_b32_e32 v45, v2
	v_mov_b32_e32 v46, v2
	v_mov_b32_e32 v47, v2
	v_mov_b32_e32 v48, v2
	v_mov_b32_e32 v49, v2
	v_mov_b32_e32 v58, v2
	v_mov_b32_e32 v59, v2
	v_mov_b32_e32 v60, v2
	v_mov_b32_e32 v61, v2
	v_mov_b32_e32 v62, v2
	v_mov_b32_e32 v63, v2
	v_mov_b32_e32 v64, v2
	v_mov_b32_e32 v65, v2
	v_mov_b32_e32 v66, v2
	v_mov_b32_e32 v67, v2
	v_mov_b32_e32 v68, v2
	v_mov_b32_e32 v69, v2
	v_mov_b32_e32 v70, v2
	v_mov_b32_e32 v71, v2
	v_mov_b32_e32 v72, v2
	v_mov_b32_e32 v73, v2
	v_mov_b32_e32 v82, v2
	v_mov_b32_e32 v83, v2
	v_mov_b32_e32 v84, v2
	v_mov_b32_e32 v85, v2
	v_mov_b32_e32 v86, v2
	v_mov_b32_e32 v87, v2
	v_mov_b32_e32 v88, v2
	v_mov_b32_e32 v89, v2
	v_mov_b32_e32 v98, v2
	v_mov_b32_e32 v99, v2
	v_mov_b32_e32 v100, v2
	v_mov_b32_e32 v101, v2
	v_mov_b32_e32 v102, v2
	v_mov_b32_e32 v103, v2
	v_mov_b32_e32 v104, v2
	v_mov_b32_e32 v105, v2
	v_mov_b32_e32 v114, v2
	v_mov_b32_e32 v115, v2
	v_mov_b32_e32 v116, v2
	v_mov_b32_e32 v117, v2
	v_mov_b32_e32 v118, v2
	v_mov_b32_e32 v119, v2
	v_mov_b32_e32 v120, v2
	v_mov_b32_e32 v121, v2
	v_mov_b32_e32 v74, v2
	v_mov_b32_e32 v75, v2
	v_mov_b32_e32 v76, v2
	v_mov_b32_e32 v77, v2
	v_mov_b32_e32 v78, v2
	v_mov_b32_e32 v79, v2
	v_mov_b32_e32 v80, v2
	v_mov_b32_e32 v81, v2
	v_mov_b32_e32 v90, v2
	v_mov_b32_e32 v91, v2
	v_mov_b32_e32 v92, v2
	v_mov_b32_e32 v93, v2
	v_mov_b32_e32 v94, v2
	v_mov_b32_e32 v95, v2
	v_mov_b32_e32 v96, v2
	v_mov_b32_e32 v97, v2
	v_mov_b32_e32 v106, v2
	v_mov_b32_e32 v107, v2
	v_mov_b32_e32 v108, v2
	v_mov_b32_e32 v109, v2
	v_mov_b32_e32 v110, v2
	v_mov_b32_e32 v111, v2
	v_mov_b32_e32 v112, v2
	v_mov_b32_e32 v113, v2
	v_mov_b32_e32 v122, v2
	v_mov_b32_e32 v123, v2
	v_mov_b32_e32 v124, v2
	v_mov_b32_e32 v125, v2
	v_mov_b32_e32 v126, v2
	v_mov_b32_e32 v127, v2
	v_mov_b32_e32 v128, v2
	v_mov_b32_e32 v129, v2
	s_cmp_lg_u32 s101, 0
	s_cbranch_scc0 .Lph1244_y

;     __host__ __device__ bool next(int i, Unit& u) const { if (!so.next(i >> 1, u)) return false; u.k0 = (i & 1) * 512; return true; }
;     __host__ __device__ bool next(int i, Unit& u) const { if (!so.next(i, u)) return false; u.pe = main_tile(u.pn); return true; }
;     __host__ __device__ bool next(int i, Unit& u) const { if (start + i * stride >= limit) return false; if (!so.next(i, u)) return false; u.pe = late_tile(u.pn); return true; }
; template <class Epi, class Sched, bool ALIGN_EPI = false, bool SP2 = false>
; __device__ __forceinline__ void gemm_phase(PG8_LAS unsigned char* lds, const Gemm g, const Sched& S, const Epi& E) {
;     ...
;         const bool has_next = S.next(ui + 1, nxt);
;         const char* nA = has_next ? (const char*)g.A + (size_t)nxt.pm * tstepA + (size_t)nxt.k0 * 2 : cA; const char* nB = has_next ? (const char*)g.Bt + (size_t)nxt.pn * tstepB + (size_t)nxt.k0 * 2 : cB;
;         for (int t = 0; t < nt; t += 2) {
;             const bool last = (t == nt - 2);
;             const char* a1 = cA + (size_t)(t + 1) * kstepA;
;             const char* a2 = last ? nA : cA + (size_t)(t + 2) * kstepA; const char* b2 = last ? nB : cB + (size_t)(t + 2) * kstep;
;             const char* a3 = a2 + kstepA; const char* b3 = b2 + kstep;
.LBB0_1338:
	s_ashr_i32 s25, s24, 31
	s_lshl_b64 s[28:29], s[24:25], 21
	s_add_u32 s28, s26, s28
	s_addc_u32 s29, s27, s29
	s_and_b64 s[30:31], s[4:5], exec
	s_cselect_b32 s25, s29, s15
	s_cselect_b32 s59, s28, s14
	s_ashr_i32 s23, s22, 31
	s_lshl_b64 s[30:31], s[22:23], 21
	s_add_u32 s30, s12, s30
	s_addc_u32 s31, s13, s31
	s_and_b64 s[36:37], s[4:5], exec
	s_cselect_b32 s23, s31, s11
	s_cselect_b32 s62, s30, s10
	s_add_u32 s63, s10, 0x100
	s_addc_u32 s64, s11, 0
	s_mov_b32 s65, -2
	s_mov_b64 s[36:37], 0x10000
	v_mov_b64_e32 v[146:147], v[140:141]
	v_mov_b64_e32 v[148:149], v[138:139]
	s_cmp_lg_u32 s101, 0
	s_cbranch_scc0 .Lph1339_y
